# attention: running-max subtraction of both row groups folded into the QK MFMA accumulator input (second block parked in LDS-freed registers)
# baseline (speedup 1.0000x reference)
.LBB0_91:
	v_mbcnt_lo_u32_b32 v209, -1, 0
	v_mbcnt_hi_u32_b32 v209, -1, v209
	v_readlane_b32 s98, v254, 54
	s_nop 3
	v_lshl_add_u32 v209, s98, 6, v209
	v_lshlrev_b32_e32 v209, 2, v209
	v_add_u32_e32 v209, 0x10000, v209
	ds_read_b32 v184, v209 offset:0
	ds_read_b32 v187, v209 offset:2048
	ds_read_b32 v188, v209 offset:4096
	ds_read_b32 v189, v209 offset:6144
	ds_read_b32 v190, v209 offset:8192
	ds_read_b32 v191, v209 offset:10240
	ds_read_b32 v192, v209 offset:12288
	ds_read_b32 v193, v209 offset:14336
	ds_read_b32 v194, v209 offset:16384
	ds_read_b32 v195, v209 offset:18432
	ds_read_b32 v196, v209 offset:20480
	ds_read_b32 v198, v209 offset:22528
	ds_read_b32 v200, v209 offset:24576
	ds_read_b32 v201, v209 offset:26624
	ds_read_b32 v202, v209 offset:28672
	ds_read_b32 v203, v209 offset:30720
	s_waitcnt lgkmcnt(0)
	ds_bpermute_b32 v0, v222, v215
	s_lshl_b32 s2, s24, 6
	s_lshl_b32 s2, s2, 1
	v_readlane_b32 s10, v255, 18
	v_readlane_b32 s11, v255, 19
	s_waitcnt lgkmcnt(0)
	v_add_f32_e32 v0, v215, v0
	v_div_scale_f32 v2, s[8:9], v0, v0, 1.0
	v_rcp_f32_e32 v3, v2
	v_div_scale_f32 v4, vcc, 1.0, v0, 1.0
	s_add_u32 s2, s10, s2
	v_fma_f32 v5, -v2, v3, 1.0
	v_fmac_f32_e32 v3, v5, v3
	v_mul_f32_e32 v5, v4, v3
	v_fma_f32 v6, -v2, v5, v4
	v_fmac_f32_e32 v5, v6, v3
	v_fma_f32 v2, -v2, v5, v4
	v_div_fmas_f32 v2, v2, v3, v5
	v_div_fixup_f32 v0, v2, v0, 1.0
	v_mul_f32_e32 v2, v64, v0
	v_mul_f32_e32 v3, v65, v0
	s_addc_u32 s3, s11, 0
	v_cvt_pk_bf16_f32 v2, v2, v3
	v_mul_f32_e32 v3, v66, v0
	v_mul_f32_e32 v4, v67, v0
	v_cvt_pk_bf16_f32 v3, v3, v4
	v_lshl_add_u64 v[4:5], s[2:3], 0, v[202:203]
	v_mov_b32_e32 v199, v1
	v_lshl_add_u64 v[4:5], v[4:5], 0, v[198:199]
	global_store_dwordx2 v[4:5], v[2:3], off
	v_mul_f32_e32 v2, v68, v0
	v_mul_f32_e32 v3, v69, v0
	v_cvt_pk_bf16_f32 v2, v2, v3
	v_mul_f32_e32 v3, v70, v0
	v_mul_f32_e32 v6, v71, v0
	v_cvt_pk_bf16_f32 v3, v3, v6
	global_store_dwordx2 v[4:5], v[2:3], off offset:16
	v_mul_f32_e32 v2, v72, v0
	v_mul_f32_e32 v3, v73, v0
	v_cvt_pk_bf16_f32 v2, v2, v3
	v_mul_f32_e32 v3, v74, v0
	v_mul_f32_e32 v6, v75, v0
	v_cvt_pk_bf16_f32 v3, v3, v6
	global_store_dwordx2 v[4:5], v[2:3], off offset:32
	v_mul_f32_e32 v2, v76, v0
	v_mul_f32_e32 v3, v77, v0
	v_cvt_pk_bf16_f32 v2, v2, v3
	v_mul_f32_e32 v3, v78, v0
	v_mul_f32_e32 v6, v79, v0
	v_cvt_pk_bf16_f32 v3, v3, v6
	global_store_dwordx2 v[4:5], v[2:3], off offset:48
	v_mul_f32_e32 v2, v48, v0
	v_mul_f32_e32 v3, v49, v0
	v_cvt_pk_bf16_f32 v2, v2, v3
	v_mul_f32_e32 v3, v50, v0
	v_mul_f32_e32 v6, v51, v0
	v_cvt_pk_bf16_f32 v3, v3, v6
	global_store_dwordx2 v[4:5], v[2:3], off offset:64
	v_mul_f32_e32 v2, v52, v0
	v_mul_f32_e32 v3, v53, v0
	v_cvt_pk_bf16_f32 v2, v2, v3
	v_mul_f32_e32 v3, v54, v0
	v_mul_f32_e32 v6, v55, v0
	v_cvt_pk_bf16_f32 v3, v3, v6
	global_store_dwordx2 v[4:5], v[2:3], off offset:80
	v_mul_f32_e32 v2, v56, v0
	v_mul_f32_e32 v3, v57, v0
	v_cvt_pk_bf16_f32 v2, v2, v3
	v_mul_f32_e32 v3, v58, v0
	v_mul_f32_e32 v6, v59, v0
	v_cvt_pk_bf16_f32 v3, v3, v6
	global_store_dwordx2 v[4:5], v[2:3], off offset:96
	ds_bpermute_b32 v3, v222, v225
	v_mul_f32_e32 v2, v60, v0
	v_mul_f32_e32 v6, v61, v0
	v_cvt_pk_bf16_f32 v2, v2, v6
	v_mul_f32_e32 v6, v62, v0
	s_waitcnt lgkmcnt(0)
	v_add_f32_e32 v7, v225, v3
	v_div_scale_f32 v8, s[8:9], v7, v7, 1.0
	v_rcp_f32_e32 v9, v8
	v_mul_f32_e32 v0, v63, v0
	v_cvt_pk_bf16_f32 v3, v6, v0
	global_store_dwordx2 v[4:5], v[2:3], off offset:112
	v_fma_f32 v0, -v8, v9, 1.0
	v_fmac_f32_e32 v9, v0, v9
	v_div_scale_f32 v0, vcc, 1.0, v7, 1.0
	v_mul_f32_e32 v2, v0, v9
	v_fma_f32 v3, -v8, v2, v0
	v_fmac_f32_e32 v2, v3, v9
	v_fma_f32 v0, -v8, v2, v0
	v_div_fmas_f32 v0, v0, v9, v2
	v_div_fixup_f32 v0, v0, v7, 1.0
	v_mul_f32_e32 v2, v32, v0
	v_mul_f32_e32 v3, v33, v0
	v_cvt_pk_bf16_f32 v2, v2, v3
	v_mul_f32_e32 v3, v34, v0
	v_mul_f32_e32 v4, v35, v0
	v_cvt_pk_bf16_f32 v3, v3, v4
	v_lshl_add_u64 v[4:5], s[2:3], 0, v[200:201]
	v_lshl_add_u64 v[4:5], v[4:5], 0, v[198:199]
	global_store_dwordx2 v[4:5], v[2:3], off
	v_mul_f32_e32 v2, v36, v0
	v_mul_f32_e32 v3, v37, v0
	v_cvt_pk_bf16_f32 v2, v2, v3
	v_mul_f32_e32 v3, v38, v0
	v_mul_f32_e32 v6, v39, v0
	v_cvt_pk_bf16_f32 v3, v3, v6
	global_store_dwordx2 v[4:5], v[2:3], off offset:16
	v_mul_f32_e32 v2, v40, v0
	v_mul_f32_e32 v3, v41, v0
	v_cvt_pk_bf16_f32 v2, v2, v3
	v_mul_f32_e32 v3, v42, v0
	v_mul_f32_e32 v6, v43, v0
	v_cvt_pk_bf16_f32 v3, v3, v6
	global_store_dwordx2 v[4:5], v[2:3], off offset:32
	v_mul_f32_e32 v2, v44, v0
	v_mul_f32_e32 v3, v45, v0
	v_cvt_pk_bf16_f32 v2, v2, v3
	v_mul_f32_e32 v3, v46, v0
	v_mul_f32_e32 v6, v47, v0
	v_cvt_pk_bf16_f32 v3, v3, v6
	global_store_dwordx2 v[4:5], v[2:3], off offset:48
	v_mul_f32_e32 v2, v16, v0
	v_mul_f32_e32 v3, v17, v0
	v_cvt_pk_bf16_f32 v2, v2, v3
	v_mul_f32_e32 v3, v18, v0
	v_mul_f32_e32 v6, v19, v0
	v_cvt_pk_bf16_f32 v3, v3, v6
	global_store_dwordx2 v[4:5], v[2:3], off offset:64
	v_mul_f32_e32 v2, v20, v0
	v_mul_f32_e32 v3, v21, v0
	v_cvt_pk_bf16_f32 v2, v2, v3
	v_mul_f32_e32 v3, v22, v0
	v_mul_f32_e32 v6, v23, v0
	v_cvt_pk_bf16_f32 v3, v3, v6
	global_store_dwordx2 v[4:5], v[2:3], off offset:80
	v_mul_f32_e32 v2, v24, v0
	v_mul_f32_e32 v3, v25, v0
	v_cvt_pk_bf16_f32 v2, v2, v3
	v_mul_f32_e32 v3, v26, v0
	v_mul_f32_e32 v6, v27, v0
	v_cvt_pk_bf16_f32 v3, v3, v6
	global_store_dwordx2 v[4:5], v[2:3], off offset:96
	v_mul_f32_e32 v2, v28, v0
	v_mul_f32_e32 v3, v29, v0
	v_cvt_pk_bf16_f32 v2, v2, v3
	v_mul_f32_e32 v3, v30, v0
	v_mul_f32_e32 v0, v31, v0
	v_cvt_pk_bf16_f32 v3, v3, v0
	global_store_dwordx2 v[4:5], v[2:3], off offset:112
	s_load_dword s2, s[74:75], 0x10
	s_waitcnt lgkmcnt(0)
	s_lshr_b32 s2, s2, 16
	s_cmp_lg_u32 s2, 0
	s_cselect_b64 s[2:3], -1, 0
	s_cmp_lg_u64 s[2:3], 0
	s_addc_u32 s47, s47, s81
	s_cmpk_gt_i32 s47, 0x47f
	s_cbranch_scc1 .LBB0_137

.LBB0_107:
	v_lshlrev_b64 v[200:201], 11, v[8:9]
	v_lshl_add_u64 v[6:7], v[6:7], 0, v[200:201]
	global_load_dwordx4 v[160:163], v[6:7], off
	global_load_dwordx4 v[164:167], v[6:7], off offset:32
	global_load_dwordx4 v[168:171], v[6:7], off offset:64
	global_load_dwordx4 v[172:175], v[6:7], off offset:96
	s_mov_b32 s25, s95
	s_lshl_b64 s[8:9], s[24:25], 2
	s_waitcnt lgkmcnt(0)
	s_add_u32 s8, s42, s8
	v_cndmask_b32_e64 v0, 0, 1, s[16:17]
	s_addc_u32 s9, s43, s9
	v_mov_b32_e32 v225, 0
	v_cmp_ne_u32_e64 s[40:41], 1, v0
	v_mov_b32_e32 v226, 0xf149f2ca
	s_andn2_b64 vcc, exec, s[16:17]
	v_mov_b32_e32 v215, 0
	v_mov_b32_e32 v227, 0xf149f2ca
	s_cbranch_vccnz .LBB0_109
	global_load_dword v0, v1, s[8:9]
	v_mov_b32_e32 v215, v187
	s_waitcnt vmcnt(0)
	v_mul_f32_e32 v227, 0x3fb8aa3b, v0

.LBB0_113:
	v_mbcnt_lo_u32_b32 v209, -1, 0
	v_mbcnt_hi_u32_b32 v209, -1, v209
	v_readlane_b32 s98, v254, 54
	s_nop 3
	v_lshl_add_u32 v209, s98, 6, v209
	v_lshlrev_b32_e32 v209, 2, v209
	v_add_u32_e32 v209, 0x10000, v209
	ds_write_b32 v209, v184 offset:0
	ds_write_b32 v209, v187 offset:2048
	ds_write_b32 v209, v188 offset:4096
	ds_write_b32 v209, v189 offset:6144
	ds_write_b32 v209, v190 offset:8192
	ds_write_b32 v209, v191 offset:10240
	ds_write_b32 v209, v192 offset:12288
	ds_write_b32 v209, v193 offset:14336
	ds_write_b32 v209, v194 offset:16384
	ds_write_b32 v209, v195 offset:18432
	ds_write_b32 v209, v196 offset:20480
	ds_write_b32 v209, v198 offset:22528
	ds_write_b32 v209, v200 offset:24576
	ds_write_b32 v209, v201 offset:26624
	ds_write_b32 v209, v202 offset:28672
	ds_write_b32 v209, v203 offset:30720
	s_cmp_lt_i32 s11, -3
	s_waitcnt lgkmcnt(0)
	s_barrier
	s_cbranch_scc1 .LBB0_90
	v_lshl_add_u64 v[8:9], s[2:3], 0, v[190:191]
	v_lshl_add_u64 v[204:205], v[8:9], 0, v[0:1]
	v_lshl_add_u64 v[206:207], v[6:7], 0, v[0:1]
	v_add_u32_e32 v0, s28, v220
	v_mov_b32_e32 v14, v1
	v_mov_b32_e32 v15, v1
	v_cndmask_b32_e64 v228, v196, v4, s[38:39]
	v_cndmask_b32_e64 v229, v194, v2, s[38:39]
	v_add_u32_e32 v230, 0xffffff80, v0
	v_add_u32_e32 v231, 0xbf, v0
	v_mov_b32_e32 v0, v1
	v_mov_b32_e32 v2, v1
	v_mov_b32_e32 v3, v1
	v_mov_b32_e32 v4, v1
	v_mov_b32_e32 v5, v1
	v_mov_b32_e32 v6, v1
	v_mov_b32_e32 v7, v1
	v_mov_b32_e32 v8, v1
	v_mov_b32_e32 v9, v1
	v_mov_b32_e32 v10, v1
	v_mov_b32_e32 v11, v1
	v_mov_b32_e32 v12, v1
	v_mov_b32_e32 v13, v1
	v_mov_b64_e32 v[78:79], v[14:15]
	v_mov_b64_e32 v[62:63], v[14:15]
	v_mov_b64_e32 v[46:47], v[14:15]
	v_mov_b64_e32 v[30:31], v[14:15]
	s_add_i32 s18, s11, 4
	s_sub_i32 s19, s10, s8
	s_mov_b32 s49, 0
	v_mov_b64_e32 v[76:77], v[12:13]
	v_mov_b64_e32 v[74:75], v[10:11]
	v_mov_b64_e32 v[72:73], v[8:9]
	v_mov_b64_e32 v[70:71], v[6:7]
	v_mov_b64_e32 v[68:69], v[4:5]
	v_mov_b64_e32 v[66:67], v[2:3]
	v_mov_b64_e32 v[64:65], v[0:1]
	v_mov_b64_e32 v[60:61], v[12:13]
	v_mov_b64_e32 v[58:59], v[10:11]
	v_mov_b64_e32 v[56:57], v[8:9]
	v_mov_b64_e32 v[54:55], v[6:7]
	v_mov_b64_e32 v[52:53], v[4:5]
	v_mov_b64_e32 v[50:51], v[2:3]
	v_mov_b64_e32 v[48:49], v[0:1]
	v_mov_b64_e32 v[44:45], v[12:13]
	v_mov_b64_e32 v[42:43], v[10:11]
	v_mov_b64_e32 v[40:41], v[8:9]
	v_mov_b64_e32 v[38:39], v[6:7]
	v_mov_b64_e32 v[36:37], v[4:5]
	v_mov_b64_e32 v[34:35], v[2:3]
	v_mov_b64_e32 v[32:33], v[0:1]
	v_mov_b64_e32 v[28:29], v[12:13]
	v_mov_b64_e32 v[26:27], v[10:11]
	v_mov_b64_e32 v[24:25], v[8:9]
	v_mov_b64_e32 v[22:23], v[6:7]
	v_mov_b64_e32 v[20:21], v[4:5]
	v_mov_b64_e32 v[18:19], v[2:3]
	v_mov_b64_e32 v[16:17], v[0:1]
	s_mov_b32 s84, 0x8000
	v_readlane_b32 s85, v255, 4
	v_readlane_b32 s94, v255, 5
	v_mov_b32_e32 v187, 0xf0c9f2ca
	v_cmp_lt_f32_e32 vcc, v226, v187
	s_nop 1
	v_cndmask_b32_e64 v184, v226, 0, vcc
	v_sub_f32_e32 v188, 0, v184
	v_sub_f32_e32 v189, 0, v184
	v_sub_f32_e32 v190, 0, v184
	v_sub_f32_e32 v191, 0, v184
	v_sub_f32_e32 v192, 0, v184
	v_sub_f32_e32 v193, 0, v184
	v_sub_f32_e32 v194, 0, v184
	v_sub_f32_e32 v195, 0, v184
	v_sub_f32_e32 v196, 0, v184
	v_sub_f32_e32 v197, 0, v184
	v_sub_f32_e32 v198, 0, v184
	v_sub_f32_e32 v199, 0, v184
	v_sub_f32_e32 v200, 0, v184
	v_sub_f32_e32 v201, 0, v184
	v_sub_f32_e32 v202, 0, v184
	v_sub_f32_e32 v203, 0, v184

.LBB0_121:
	s_and_saveexec_b64 s[44:45], s[8:9]
	s_cbranch_execz .LBB0_131
	s_bitcmp1_b32 s49, 0
	s_cselect_b32 s8, 0x4800, 0
	s_add_i32 s8, s8, 16
	v_add3_u32 v0, s8, v186, v224
	ds_read_b128 v[2:5], v0
	s_and_b64 s[2:3], s[16:17], s[2:3]
	v_cndmask_b32_e64 v6, 0, 1, s[2:3]
	v_cmp_ne_u32_e64 s[38:39], 1, v6
	s_andn2_b64 vcc, exec, s[2:3]
	ds_read_b128 v[6:9], v0 offset:32
	ds_read_b128 v[10:13], v0 offset:64
	s_waitcnt lgkmcnt(2)
	v_mfma_f32_32x32x16_bf16 v[112:127], v[2:5], v[144:147], v[234:249]
	v_mfma_f32_32x32x16_bf16 v[96:111], v[2:5], v[160:163], v[188:203]
	ds_read_b128 v[2:5], v0 offset:96
	s_waitcnt lgkmcnt(2)
	v_mfma_f32_32x32x16_bf16 v[112:127], v[6:9], v[148:151], v[112:127]
	v_mfma_f32_32x32x16_bf16 v[96:111], v[6:9], v[164:167], v[96:111]
	ds_read_b128 v[6:9], v0 offset:4608
	s_waitcnt lgkmcnt(2)
	v_mfma_f32_32x32x16_bf16 v[112:127], v[10:13], v[152:155], v[112:127]
	v_mfma_f32_32x32x16_bf16 v[96:111], v[10:13], v[168:171], v[96:111]
	ds_read_b128 v[10:13], v0 offset:4640
	s_waitcnt lgkmcnt(2)
	v_mfma_f32_32x32x16_bf16 v[112:127], v[2:5], v[156:159], v[112:127]
	v_mfma_f32_32x32x16_bf16 v[96:111], v[2:5], v[172:175], v[96:111]
	ds_read_b128 v[2:5], v0 offset:4672
	s_waitcnt lgkmcnt(2)
	v_mfma_f32_32x32x16_bf16 v[128:143], v[6:9], v[144:147], v[234:249]
	v_mfma_f32_32x32x16_bf16 v[80:95], v[6:9], v[160:163], v[188:203]
	ds_read_b128 v[6:9], v0 offset:4704
	v_add_u32_e32 v0, s48, v221
	s_waitcnt lgkmcnt(2)
	v_mfma_f32_32x32x16_bf16 v[128:143], v[10:13], v[148:151], v[128:143]
	v_mfma_f32_32x32x16_bf16 v[80:95], v[10:13], v[164:167], v[80:95]
	s_waitcnt lgkmcnt(1)
	v_mfma_f32_32x32x16_bf16 v[128:143], v[2:5], v[152:155], v[128:143]
	v_mfma_f32_32x32x16_bf16 v[80:95], v[2:5], v[168:171], v[80:95]
	s_waitcnt lgkmcnt(0)
	v_mfma_f32_32x32x16_bf16 v[128:143], v[6:9], v[156:159], v[128:143]
	v_mfma_f32_32x32x16_bf16 v[80:95], v[6:9], v[172:175], v[80:95]
	s_cbranch_vccnz .LBB0_124
	v_sub_u32_e32 v2, v0, v229
	s_movk_i32 s0, 0xfefe
	v_cmp_lt_u32_e32 vcc, s0, v2
	v_add_u32_e32 v3, 1, v2
	s_nop 0
	v_cndmask_b32_e32 v112, v210, v112, vcc
	v_cmp_lt_u32_e32 vcc, s0, v3
	v_add_u32_e32 v3, 2, v2
	s_nop 0
	v_cndmask_b32_e32 v113, v210, v113, vcc
	v_cmp_lt_u32_e32 vcc, s0, v3
	v_add_u32_e32 v3, 3, v2
	s_nop 0
	v_cndmask_b32_e32 v114, v210, v114, vcc
	v_cmp_lt_u32_e32 vcc, s0, v3
	v_add_u32_e32 v3, 8, v2
	s_nop 0
	v_cndmask_b32_e32 v115, v210, v115, vcc
	v_cmp_lt_u32_e32 vcc, s0, v3
	v_add_u32_e32 v3, 9, v2
	s_nop 0
	v_cndmask_b32_e32 v116, v210, v116, vcc
	v_cmp_lt_u32_e32 vcc, s0, v3
	v_add_u32_e32 v3, 10, v2
	s_nop 0
	v_cndmask_b32_e32 v117, v210, v117, vcc
	v_cmp_lt_u32_e32 vcc, s0, v3
	v_add_u32_e32 v3, 11, v2
	s_nop 0
	v_cndmask_b32_e32 v118, v210, v118, vcc
	v_cmp_lt_u32_e32 vcc, s0, v3
	v_add_u32_e32 v3, 16, v2
	s_nop 0
	v_cndmask_b32_e32 v119, v210, v119, vcc
	v_cmp_lt_u32_e32 vcc, s0, v3
	v_add_u32_e32 v3, 17, v2
	s_nop 0
	v_cndmask_b32_e32 v120, v210, v120, vcc
	v_cmp_lt_u32_e32 vcc, s0, v3
	v_add_u32_e32 v3, 18, v2
	s_nop 0
	v_cndmask_b32_e32 v121, v210, v121, vcc
	v_cmp_lt_u32_e32 vcc, s0, v3
	v_add_u32_e32 v3, 19, v2
	s_nop 0
	v_cndmask_b32_e32 v122, v210, v122, vcc
	v_cmp_lt_u32_e32 vcc, s0, v3
	v_add_u32_e32 v3, 24, v2
	s_nop 0
	v_cndmask_b32_e32 v123, v210, v123, vcc
	v_cmp_lt_u32_e32 vcc, s0, v3
	v_add_u32_e32 v3, 25, v2
	s_nop 0
	v_cndmask_b32_e32 v124, v210, v124, vcc
	v_cmp_lt_u32_e32 vcc, s0, v3
	v_add_u32_e32 v3, 26, v2
	s_nop 0
	v_cndmask_b32_e32 v125, v210, v125, vcc
	v_cmp_lt_u32_e32 vcc, s0, v3
	v_add_u32_e32 v3, 27, v2
	s_nop 0
	v_cndmask_b32_e32 v126, v210, v126, vcc
	v_cmp_lt_u32_e32 vcc, s0, v3
	v_add_u32_e32 v3, 32, v2
	s_nop 0
	v_cndmask_b32_e32 v127, v210, v127, vcc
	v_cmp_lt_u32_e32 vcc, s0, v3
	v_add_u32_e32 v3, 33, v2
	s_nop 0
	v_cndmask_b32_e32 v128, v210, v128, vcc
	v_cmp_lt_u32_e32 vcc, s0, v3
	v_add_u32_e32 v3, 34, v2
	s_nop 0
	v_cndmask_b32_e32 v129, v210, v129, vcc
	v_cmp_lt_u32_e32 vcc, s0, v3
	v_add_u32_e32 v3, 35, v2
	s_nop 0
	v_cndmask_b32_e32 v130, v210, v130, vcc
	v_cmp_lt_u32_e32 vcc, s0, v3
	v_add_u32_e32 v3, 40, v2
	s_nop 0
	v_cndmask_b32_e32 v131, v210, v131, vcc
	v_cmp_lt_u32_e32 vcc, s0, v3
	v_add_u32_e32 v3, 41, v2
	s_nop 0
	v_cndmask_b32_e32 v132, v210, v132, vcc
	v_cmp_lt_u32_e32 vcc, s0, v3
	v_add_u32_e32 v3, 42, v2
	s_nop 0
	v_cndmask_b32_e32 v133, v210, v133, vcc
	v_cmp_lt_u32_e32 vcc, s0, v3
	v_add_u32_e32 v3, 43, v2
	s_nop 0
	v_cndmask_b32_e32 v134, v210, v134, vcc
	v_cmp_lt_u32_e32 vcc, s0, v3
	v_add_u32_e32 v3, 48, v2
	s_nop 0
	v_cndmask_b32_e32 v135, v210, v135, vcc
	v_cmp_lt_u32_e32 vcc, s0, v3
	v_add_u32_e32 v3, 49, v2
	s_nop 0
	v_cndmask_b32_e32 v136, v210, v136, vcc
	v_cmp_lt_u32_e32 vcc, s0, v3
	v_add_u32_e32 v3, 50, v2
	s_nop 0
	v_cndmask_b32_e32 v137, v210, v137, vcc
	v_cmp_lt_u32_e32 vcc, s0, v3
	v_add_u32_e32 v3, 51, v2
	s_nop 0
	v_cndmask_b32_e32 v138, v210, v138, vcc
	v_cmp_lt_u32_e32 vcc, s0, v3
	v_add_u32_e32 v3, 56, v2
	s_nop 0
	v_cndmask_b32_e32 v139, v210, v139, vcc
	v_cmp_lt_u32_e32 vcc, s0, v3
	v_add_u32_e32 v3, 57, v2
	s_nop 0
	v_cndmask_b32_e32 v140, v210, v140, vcc
	v_cmp_lt_u32_e32 vcc, s0, v3
	v_add_u32_e32 v3, 58, v2
	v_add_u32_e32 v2, 59, v2
	v_cndmask_b32_e32 v141, v210, v141, vcc
	v_cmp_lt_u32_e32 vcc, s0, v3
	s_nop 1
	v_cndmask_b32_e32 v142, v210, v142, vcc
	v_cmp_lt_u32_e32 vcc, s0, v2
	s_nop 1
	v_cndmask_b32_e32 v143, v210, v143, vcc
.LBB0_124:
	v_max_f32_e32 v2, v113, v113
	v_max_f32_e32 v3, v112, v112
	v_max_f32_e32 v2, v3, v2
	v_max3_f32 v2, v2, v114, v115
	v_max3_f32 v2, v2, v116, v117
	v_max3_f32 v2, v2, v118, v119
	v_max3_f32 v2, v2, v120, v121
	v_max3_f32 v2, v2, v122, v123
	v_max3_f32 v2, v2, v124, v125
	v_max3_f32 v2, v2, v126, v127
	v_max3_f32 v2, v2, v128, v129
	v_max3_f32 v2, v2, v130, v131
	v_max3_f32 v2, v2, v132, v133
	v_max3_f32 v2, v2, v134, v135
	v_max3_f32 v2, v2, v136, v137
	v_max3_f32 v2, v2, v138, v139
	v_max3_f32 v2, v2, v140, v141
	v_max3_f32 v2, v2, v142, v143
	v_add_f32_e32 v2, v2, v208
	v_add_f32_e32 v3, 0x41000000, v227
	v_cmp_gt_f32_e32 vcc, v2, v3
	s_cbranch_vccz .LBB0_126
	v_max_f32_e32 v2, v2, v2
	v_max_f32_e32 v3, v227, v227
	v_max_f32_e32 v2, v3, v2
	ds_bpermute_b32 v3, v222, v2
	s_waitcnt lgkmcnt(0)
	v_max_f32_e32 v3, v3, v3
	v_max_f32_e32 v3, v2, v3
	v_sub_f32_e32 v2, v227, v3
	v_exp_f32_e32 v2, v2
	v_mov_b32_e32 v227, v3
	v_mul_f32_e32 v215, v215, v2
	v_pk_mul_f32 v[78:79], v[78:79], v[2:3] op_sel_hi:[1,0]
	v_pk_mul_f32 v[76:77], v[76:77], v[2:3] op_sel_hi:[1,0]
	v_pk_mul_f32 v[74:75], v[74:75], v[2:3] op_sel_hi:[1,0]
	v_pk_mul_f32 v[72:73], v[72:73], v[2:3] op_sel_hi:[1,0]
	v_pk_mul_f32 v[70:71], v[70:71], v[2:3] op_sel_hi:[1,0]
	v_pk_mul_f32 v[68:69], v[68:69], v[2:3] op_sel_hi:[1,0]
	v_pk_mul_f32 v[66:67], v[66:67], v[2:3] op_sel_hi:[1,0]
	v_pk_mul_f32 v[64:65], v[64:65], v[2:3] op_sel_hi:[1,0]
	v_pk_mul_f32 v[62:63], v[62:63], v[2:3] op_sel_hi:[1,0]
	v_pk_mul_f32 v[60:61], v[60:61], v[2:3] op_sel_hi:[1,0]
	v_pk_mul_f32 v[58:59], v[58:59], v[2:3] op_sel_hi:[1,0]
	v_pk_mul_f32 v[56:57], v[56:57], v[2:3] op_sel_hi:[1,0]
	v_pk_mul_f32 v[54:55], v[54:55], v[2:3] op_sel_hi:[1,0]
	v_pk_mul_f32 v[52:53], v[52:53], v[2:3] op_sel_hi:[1,0]
	v_pk_mul_f32 v[50:51], v[50:51], v[2:3] op_sel_hi:[1,0]
	v_pk_mul_f32 v[48:49], v[48:49], v[2:3] op_sel_hi:[1,0]
	v_sub_f32_e32 v209, v227, v208
	v_mov_b32_e32 v208, v227
	v_sub_f32_e32 v112, v112, v209
	v_sub_f32_e32 v113, v113, v209
	v_sub_f32_e32 v114, v114, v209
	v_sub_f32_e32 v115, v115, v209
	v_sub_f32_e32 v116, v116, v209
	v_sub_f32_e32 v117, v117, v209
	v_sub_f32_e32 v118, v118, v209
	v_sub_f32_e32 v119, v119, v209
	v_sub_f32_e32 v120, v120, v209
	v_sub_f32_e32 v121, v121, v209
	v_sub_f32_e32 v122, v122, v209
	v_sub_f32_e32 v123, v123, v209
	v_sub_f32_e32 v124, v124, v209
	v_sub_f32_e32 v125, v125, v209
	v_sub_f32_e32 v126, v126, v209
	v_sub_f32_e32 v127, v127, v209
	v_sub_f32_e32 v128, v128, v209
	v_sub_f32_e32 v129, v129, v209
	v_sub_f32_e32 v130, v130, v209
	v_sub_f32_e32 v131, v131, v209
	v_sub_f32_e32 v132, v132, v209
	v_sub_f32_e32 v133, v133, v209
	v_sub_f32_e32 v134, v134, v209
	v_sub_f32_e32 v135, v135, v209
	v_sub_f32_e32 v136, v136, v209
	v_sub_f32_e32 v137, v137, v209
	v_sub_f32_e32 v138, v138, v209
	v_sub_f32_e32 v139, v139, v209
	v_sub_f32_e32 v140, v140, v209
	v_sub_f32_e32 v141, v141, v209
	v_sub_f32_e32 v142, v142, v209
	v_sub_f32_e32 v143, v143, v209
	v_sub_f32_e32 v234, 0, v208
	v_sub_f32_e32 v235, 0, v208
	v_sub_f32_e32 v236, 0, v208
	v_sub_f32_e32 v237, 0, v208
	v_sub_f32_e32 v238, 0, v208
	v_sub_f32_e32 v239, 0, v208
	v_sub_f32_e32 v240, 0, v208
	v_sub_f32_e32 v241, 0, v208
	v_sub_f32_e32 v242, 0, v208
	v_sub_f32_e32 v243, 0, v208
	v_sub_f32_e32 v244, 0, v208
	v_sub_f32_e32 v245, 0, v208
	v_sub_f32_e32 v246, 0, v208
	v_sub_f32_e32 v247, 0, v208
	v_sub_f32_e32 v248, 0, v208
	v_sub_f32_e32 v249, 0, v208
.LBB0_126:
	v_exp_f32_e32 v14, v112
	v_exp_f32_e32 v15, v113
	v_exp_f32_e32 v232, v114
	v_exp_f32_e32 v233, v115
	v_exp_f32_e32 v116, v116
	v_exp_f32_e32 v117, v117
	v_exp_f32_e32 v118, v118
	v_exp_f32_e32 v119, v119
	v_exp_f32_e32 v120, v120
	v_exp_f32_e32 v121, v121
	v_exp_f32_e32 v122, v122
	v_exp_f32_e32 v123, v123
	v_exp_f32_e32 v124, v124
	v_exp_f32_e32 v125, v125
	v_exp_f32_e32 v126, v126
	v_exp_f32_e32 v127, v127
	v_exp_f32_e32 v128, v128
	v_exp_f32_e32 v129, v129
	v_exp_f32_e32 v130, v130
	v_exp_f32_e32 v131, v131
	v_exp_f32_e32 v132, v132
	v_exp_f32_e32 v133, v133
	v_exp_f32_e32 v134, v134
	v_exp_f32_e32 v135, v135
	v_exp_f32_e32 v136, v136
	v_exp_f32_e32 v137, v137
	v_exp_f32_e32 v138, v138
	v_exp_f32_e32 v139, v139
	v_exp_f32_e32 v140, v140
	v_exp_f32_e32 v141, v141
	v_exp_f32_e32 v142, v142
	v_exp_f32_e32 v143, v143
	s_and_b64 vcc, exec, s[38:39]
	v_cvt_pk_bf16_f32 v112, v14, v15
	v_cvt_pk_bf16_f32 v113, v232, v233
	v_cvt_pk_bf16_f32 v114, v116, v117
	v_cvt_pk_bf16_f32 v115, v118, v119
	v_cvt_pk_bf16_f32 v10, v120, v121
	v_cvt_pk_bf16_f32 v11, v122, v123
	v_cvt_pk_bf16_f32 v12, v124, v125
	v_cvt_pk_bf16_f32 v13, v126, v127
	v_cvt_pk_bf16_f32 v6, v128, v129
	v_cvt_pk_bf16_f32 v7, v130, v131
	v_cvt_pk_bf16_f32 v8, v132, v133
	v_cvt_pk_bf16_f32 v9, v134, v135
	v_cvt_pk_bf16_f32 v2, v136, v137
	v_cvt_pk_bf16_f32 v3, v138, v139
	v_cvt_pk_bf16_f32 v4, v140, v141
	v_cvt_pk_bf16_f32 v5, v142, v143
	s_cbranch_vccnz .LBB0_128
	v_sub_u32_e32 v0, v0, v228
	s_movk_i32 s0, 0xfefe
	v_cmp_lt_u32_e32 vcc, s0, v0
	v_add_u32_e32 v214, 1, v0
	s_nop 0
	v_cndmask_b32_e32 v96, v210, v96, vcc
	v_cmp_lt_u32_e32 vcc, s0, v214
	v_add_u32_e32 v214, 2, v0
	s_nop 0
	v_cndmask_b32_e32 v97, v210, v97, vcc
	v_cmp_lt_u32_e32 vcc, s0, v214
	v_add_u32_e32 v214, 3, v0
	s_nop 0
	v_cndmask_b32_e32 v98, v210, v98, vcc
	v_cmp_lt_u32_e32 vcc, s0, v214
	v_add_u32_e32 v214, 8, v0
	s_nop 0
	v_cndmask_b32_e32 v99, v210, v99, vcc
	v_cmp_lt_u32_e32 vcc, s0, v214
	v_add_u32_e32 v214, 9, v0
	s_nop 0
	v_cndmask_b32_e32 v100, v210, v100, vcc
	v_cmp_lt_u32_e32 vcc, s0, v214
	v_add_u32_e32 v214, 10, v0
	s_nop 0
	v_cndmask_b32_e32 v101, v210, v101, vcc
	v_cmp_lt_u32_e32 vcc, s0, v214
	v_add_u32_e32 v214, 11, v0
	s_nop 0
	v_cndmask_b32_e32 v102, v210, v102, vcc
	v_cmp_lt_u32_e32 vcc, s0, v214
	v_add_u32_e32 v214, 16, v0
	s_nop 0
	v_cndmask_b32_e32 v103, v210, v103, vcc
	v_cmp_lt_u32_e32 vcc, s0, v214
	v_add_u32_e32 v214, 17, v0
	s_nop 0
	v_cndmask_b32_e32 v104, v210, v104, vcc
	v_cmp_lt_u32_e32 vcc, s0, v214
	v_add_u32_e32 v214, 18, v0
	s_nop 0
	v_cndmask_b32_e32 v105, v210, v105, vcc
	v_cmp_lt_u32_e32 vcc, s0, v214
	v_add_u32_e32 v214, 19, v0
	s_nop 0
	v_cndmask_b32_e32 v106, v210, v106, vcc
	v_cmp_lt_u32_e32 vcc, s0, v214
	v_add_u32_e32 v214, 24, v0
	s_nop 0
	v_cndmask_b32_e32 v107, v210, v107, vcc
	v_cmp_lt_u32_e32 vcc, s0, v214
	v_add_u32_e32 v214, 25, v0
	s_nop 0
	v_cndmask_b32_e32 v108, v210, v108, vcc
	v_cmp_lt_u32_e32 vcc, s0, v214
	v_add_u32_e32 v214, 26, v0
	s_nop 0
	v_cndmask_b32_e32 v109, v210, v109, vcc
	v_cmp_lt_u32_e32 vcc, s0, v214
	v_add_u32_e32 v214, 27, v0
	s_nop 0
	v_cndmask_b32_e32 v110, v210, v110, vcc
	v_cmp_lt_u32_e32 vcc, s0, v214
	v_add_u32_e32 v214, 32, v0
	s_nop 0
	v_cndmask_b32_e32 v111, v210, v111, vcc
	v_cmp_lt_u32_e32 vcc, s0, v214
	v_add_u32_e32 v214, 33, v0
	s_nop 0
	v_cndmask_b32_e32 v80, v210, v80, vcc
	v_cmp_lt_u32_e32 vcc, s0, v214
	v_add_u32_e32 v214, 34, v0
	s_nop 0
	v_cndmask_b32_e32 v81, v210, v81, vcc
	v_cmp_lt_u32_e32 vcc, s0, v214
	v_add_u32_e32 v214, 35, v0
	s_nop 0
	v_cndmask_b32_e32 v82, v210, v82, vcc
	v_cmp_lt_u32_e32 vcc, s0, v214
	v_add_u32_e32 v214, 40, v0
	s_nop 0
	v_cndmask_b32_e32 v83, v210, v83, vcc
	v_cmp_lt_u32_e32 vcc, s0, v214
	v_add_u32_e32 v214, 41, v0
	s_nop 0
	v_cndmask_b32_e32 v84, v210, v84, vcc
	v_cmp_lt_u32_e32 vcc, s0, v214
	v_add_u32_e32 v214, 42, v0
	s_nop 0
	v_cndmask_b32_e32 v85, v210, v85, vcc
	v_cmp_lt_u32_e32 vcc, s0, v214
	v_add_u32_e32 v214, 43, v0
	s_nop 0
	v_cndmask_b32_e32 v86, v210, v86, vcc
	v_cmp_lt_u32_e32 vcc, s0, v214
	v_add_u32_e32 v214, 48, v0
	s_nop 0
	v_cndmask_b32_e32 v87, v210, v87, vcc
	v_cmp_lt_u32_e32 vcc, s0, v214
	v_add_u32_e32 v214, 49, v0
	s_nop 0
	v_cndmask_b32_e32 v88, v210, v88, vcc
	v_cmp_lt_u32_e32 vcc, s0, v214
	v_add_u32_e32 v214, 50, v0
	s_nop 0
	v_cndmask_b32_e32 v89, v210, v89, vcc
	v_cmp_lt_u32_e32 vcc, s0, v214
	v_add_u32_e32 v214, 51, v0
	s_nop 0
	v_cndmask_b32_e32 v90, v210, v90, vcc
	v_cmp_lt_u32_e32 vcc, s0, v214
	v_add_u32_e32 v214, 56, v0
	s_nop 0
	v_cndmask_b32_e32 v91, v210, v91, vcc
	v_cmp_lt_u32_e32 vcc, s0, v214
	v_add_u32_e32 v214, 57, v0
	s_nop 0
	v_cndmask_b32_e32 v92, v210, v92, vcc
	v_cmp_lt_u32_e32 vcc, s0, v214
	v_add_u32_e32 v214, 58, v0
	v_add_u32_e32 v0, 59, v0
	v_cndmask_b32_e32 v93, v210, v93, vcc
	v_cmp_lt_u32_e32 vcc, s0, v214
	s_nop 1
	v_cndmask_b32_e32 v94, v210, v94, vcc
	v_cmp_lt_u32_e32 vcc, s0, v0
	s_nop 1
	v_cndmask_b32_e32 v95, v210, v95, vcc
.LBB0_128:
	v_max_f32_e32 v0, v97, v97
	v_max_f32_e32 v214, v96, v96
	v_max_f32_e32 v0, v214, v0
	v_max3_f32 v0, v0, v98, v99
	v_max3_f32 v0, v0, v100, v101
	v_max3_f32 v0, v0, v102, v103
	v_max3_f32 v0, v0, v104, v105
	v_max3_f32 v0, v0, v106, v107
	v_max3_f32 v0, v0, v108, v109
	v_max3_f32 v0, v0, v110, v111
	v_max3_f32 v0, v0, v80, v81
	v_max3_f32 v0, v0, v82, v83
	v_max3_f32 v0, v0, v84, v85
	v_max3_f32 v0, v0, v86, v87
	v_max3_f32 v0, v0, v88, v89
	v_max3_f32 v0, v0, v90, v91
	v_max3_f32 v0, v0, v92, v93
	v_max3_f32 v0, v0, v94, v95
	v_add_f32_e32 v0, v0, v184
	v_add_f32_e32 v214, 0x41000000, v226
	v_cmp_gt_f32_e32 vcc, v0, v214
	s_cbranch_vccz .LBB0_130
	v_max_f32_e32 v0, v0, v0
	v_max_f32_e32 v214, v226, v226
	v_max_f32_e32 v0, v214, v0
	ds_bpermute_b32 v214, v222, v0
	s_waitcnt lgkmcnt(0)
	v_max_f32_e32 v214, v214, v214
	v_max_f32_e32 v214, v0, v214
	v_sub_f32_e32 v0, v226, v214
	v_exp_f32_e32 v0, v0
	v_mov_b32_e32 v226, v214
	v_mul_f32_e32 v225, v225, v0
	v_pk_mul_f32 v[46:47], v[46:47], v[0:1] op_sel_hi:[1,0]
	v_pk_mul_f32 v[44:45], v[44:45], v[0:1] op_sel_hi:[1,0]
	v_pk_mul_f32 v[42:43], v[42:43], v[0:1] op_sel_hi:[1,0]
	v_pk_mul_f32 v[40:41], v[40:41], v[0:1] op_sel_hi:[1,0]
	v_pk_mul_f32 v[38:39], v[38:39], v[0:1] op_sel_hi:[1,0]
	v_pk_mul_f32 v[36:37], v[36:37], v[0:1] op_sel_hi:[1,0]
	v_pk_mul_f32 v[34:35], v[34:35], v[0:1] op_sel_hi:[1,0]
	v_pk_mul_f32 v[32:33], v[32:33], v[0:1] op_sel_hi:[1,0]
	v_pk_mul_f32 v[30:31], v[30:31], v[0:1] op_sel_hi:[1,0]
	v_pk_mul_f32 v[28:29], v[28:29], v[0:1] op_sel_hi:[1,0]
	v_pk_mul_f32 v[26:27], v[26:27], v[0:1] op_sel_hi:[1,0]
	v_pk_mul_f32 v[24:25], v[24:25], v[0:1] op_sel_hi:[1,0]
	v_pk_mul_f32 v[22:23], v[22:23], v[0:1] op_sel_hi:[1,0]
	v_pk_mul_f32 v[20:21], v[20:21], v[0:1] op_sel_hi:[1,0]
	v_pk_mul_f32 v[18:19], v[18:19], v[0:1] op_sel_hi:[1,0]
	v_pk_mul_f32 v[16:17], v[16:17], v[0:1] op_sel_hi:[1,0]
	v_sub_f32_e32 v187, v226, v184
	v_mov_b32_e32 v184, v226
	v_sub_f32_e32 v96, v96, v187
	v_sub_f32_e32 v97, v97, v187
	v_sub_f32_e32 v98, v98, v187
	v_sub_f32_e32 v99, v99, v187
	v_sub_f32_e32 v100, v100, v187
	v_sub_f32_e32 v101, v101, v187
	v_sub_f32_e32 v102, v102, v187
	v_sub_f32_e32 v103, v103, v187
	v_sub_f32_e32 v104, v104, v187
	v_sub_f32_e32 v105, v105, v187
	v_sub_f32_e32 v106, v106, v187
	v_sub_f32_e32 v107, v107, v187
	v_sub_f32_e32 v108, v108, v187
	v_sub_f32_e32 v109, v109, v187
	v_sub_f32_e32 v110, v110, v187
	v_sub_f32_e32 v111, v111, v187
	v_sub_f32_e32 v80, v80, v187
	v_sub_f32_e32 v81, v81, v187
	v_sub_f32_e32 v82, v82, v187
	v_sub_f32_e32 v83, v83, v187
	v_sub_f32_e32 v84, v84, v187
	v_sub_f32_e32 v85, v85, v187
	v_sub_f32_e32 v86, v86, v187
	v_sub_f32_e32 v87, v87, v187
	v_sub_f32_e32 v88, v88, v187
	v_sub_f32_e32 v89, v89, v187
	v_sub_f32_e32 v90, v90, v187
	v_sub_f32_e32 v91, v91, v187
	v_sub_f32_e32 v92, v92, v187
	v_sub_f32_e32 v93, v93, v187
	v_sub_f32_e32 v94, v94, v187
	v_sub_f32_e32 v95, v95, v187
	v_sub_f32_e32 v188, 0, v184
	v_sub_f32_e32 v189, 0, v184
	v_sub_f32_e32 v190, 0, v184
	v_sub_f32_e32 v191, 0, v184
	v_sub_f32_e32 v192, 0, v184
	v_sub_f32_e32 v193, 0, v184
	v_sub_f32_e32 v194, 0, v184
	v_sub_f32_e32 v195, 0, v184
	v_sub_f32_e32 v196, 0, v184
	v_sub_f32_e32 v197, 0, v184
	v_sub_f32_e32 v198, 0, v184
	v_sub_f32_e32 v199, 0, v184
	v_sub_f32_e32 v200, 0, v184
	v_sub_f32_e32 v201, 0, v184
	v_sub_f32_e32 v202, 0, v184
	v_sub_f32_e32 v203, 0, v184
.LBB0_130:
	v_add_f32_e32 v0, v215, v14
	v_add_f32_e32 v0, v15, v0
	v_add_f32_e32 v0, v232, v0
	v_add_f32_e32 v0, v233, v0
	v_add_f32_e32 v0, v116, v0
	v_add_f32_e32 v0, v117, v0
	v_add_f32_e32 v0, v118, v0
	v_add_f32_e32 v0, v119, v0
	v_add_f32_e32 v0, v120, v0
	v_add_f32_e32 v0, v121, v0
	v_add_f32_e32 v0, v122, v0
	v_add_f32_e32 v0, v123, v0
	v_add_f32_e32 v0, v124, v0
	v_add_f32_e32 v0, v125, v0
	v_add_f32_e32 v0, v126, v0
	v_add_f32_e32 v0, v127, v0
	v_add_f32_e32 v0, v128, v0
	v_add_f32_e32 v0, v129, v0
	v_add_f32_e32 v0, v130, v0
	v_add_f32_e32 v0, v131, v0
	v_add_f32_e32 v0, v132, v0
	v_add_f32_e32 v0, v133, v0
	v_add_f32_e32 v0, v134, v0
	v_add_f32_e32 v0, v135, v0
	v_add_f32_e32 v0, v136, v0
	v_add_f32_e32 v0, v137, v0
	v_add_f32_e32 v0, v138, v0
	v_add_f32_e32 v0, v139, v0
	v_add_f32_e32 v0, v140, v0
	v_add_f32_e32 v0, v141, v0
	v_add_f32_e32 v0, v142, v0
	v_add_f32_e32 v215, v143, v0
	v_exp_f32_e32 v0, v96
	v_exp_f32_e32 v15, v97
	v_exp_f32_e32 v96, v98
	v_exp_f32_e32 v97, v99
	v_add_f32_e32 v14, v225, v0
	v_exp_f32_e32 v98, v100
	v_add_f32_e32 v14, v15, v14
	v_exp_f32_e32 v99, v101
	v_add_f32_e32 v14, v96, v14
	v_exp_f32_e32 v100, v102
	v_add_f32_e32 v14, v97, v14
	v_exp_f32_e32 v101, v103
	v_add_f32_e32 v14, v98, v14
	v_exp_f32_e32 v102, v104
	v_add_f32_e32 v14, v99, v14
	v_exp_f32_e32 v103, v105
	v_add_f32_e32 v14, v100, v14
	v_exp_f32_e32 v104, v106
	v_add_f32_e32 v14, v101, v14
	v_exp_f32_e32 v105, v107
	v_add_f32_e32 v14, v102, v14
	v_exp_f32_e32 v106, v108
	v_add_f32_e32 v14, v103, v14
	v_exp_f32_e32 v107, v109
	v_add_f32_e32 v14, v104, v14
	v_exp_f32_e32 v108, v110
	v_add_f32_e32 v14, v105, v14
	v_exp_f32_e32 v109, v111
	v_add_f32_e32 v14, v106, v14
	v_exp_f32_e32 v80, v80
	v_add_f32_e32 v14, v107, v14
	v_exp_f32_e32 v81, v81
	v_add_f32_e32 v14, v108, v14
	v_exp_f32_e32 v82, v82
	v_add_f32_e32 v14, v109, v14
	v_exp_f32_e32 v83, v83
	v_add_f32_e32 v14, v80, v14
	v_exp_f32_e32 v110, v84
	v_add_f32_e32 v14, v81, v14
	v_exp_f32_e32 v111, v85
	v_add_f32_e32 v14, v82, v14
	v_exp_f32_e32 v116, v86
	v_add_f32_e32 v14, v83, v14
	v_exp_f32_e32 v87, v87
	v_add_f32_e32 v14, v110, v14
	v_exp_f32_e32 v117, v88
	v_add_f32_e32 v14, v111, v14
	v_exp_f32_e32 v118, v89
	v_add_f32_e32 v14, v116, v14
	v_exp_f32_e32 v119, v90
	v_add_f32_e32 v14, v87, v14
	v_exp_f32_e32 v120, v91
	v_add_f32_e32 v14, v117, v14
	v_exp_f32_e32 v121, v92
	v_add_f32_e32 v14, v118, v14
	v_exp_f32_e32 v122, v93
	v_add_f32_e32 v14, v119, v14
	v_exp_f32_e32 v123, v94
	v_add_f32_e32 v14, v120, v14
	v_exp_f32_e32 v124, v95
	v_add_f32_e32 v14, v121, v14
	v_add_f32_e32 v14, v122, v14
	v_add_f32_e32 v14, v123, v14
	v_cvt_pk_bf16_f32 v92, v0, v15
	v_add3_u32 v0, s8, v218, v224
	v_add_f32_e32 v225, v124, v14
	v_add_u32_e32 v14, 0x2000, v0
	v_cvt_pk_bf16_f32 v93, v96, v97
	v_cvt_pk_bf16_f32 v94, v98, v99
	v_cvt_pk_bf16_f32 v95, v100, v101
	v_cvt_pk_bf16_f32 v88, v102, v103
	ds_read2_b64 v[96:99], v14 offset0:128 offset1:130
	ds_read2_b64 v[100:103], v14 offset0:132 offset1:134
	v_add_u32_e32 v0, 0x3000, v0
	s_waitcnt lgkmcnt(1)
	v_mfma_f32_32x32x16_bf16 v[64:79], v[96:99], v[112:115], v[64:79]
	v_cvt_pk_bf16_f32 v89, v104, v105
	v_cvt_pk_bf16_f32 v90, v106, v107
	v_cvt_pk_bf16_f32 v91, v108, v109
	v_cvt_pk_bf16_f32 v84, v80, v81
	v_cvt_pk_bf16_f32 v85, v82, v83
	v_cvt_pk_bf16_f32 v86, v110, v111
	v_cvt_pk_bf16_f32 v87, v116, v87
	v_mfma_f32_32x32x16_bf16 v[32:47], v[96:99], v[92:95], v[32:47]
	ds_read2_b64 v[96:99], v0 offset0:192 offset1:194
	v_cvt_pk_bf16_f32 v80, v117, v118
	v_cvt_pk_bf16_f32 v81, v119, v120
	v_cvt_pk_bf16_f32 v82, v121, v122
	v_cvt_pk_bf16_f32 v83, v123, v124
	s_waitcnt lgkmcnt(0)
	v_mfma_f32_32x32x16_bf16 v[16:31], v[96:99], v[92:95], v[16:31]
	ds_read2_b64 v[92:95], v0 offset0:196 offset1:198
	v_mfma_f32_32x32x16_bf16 v[48:63], v[96:99], v[112:115], v[48:63]
	v_mfma_f32_32x32x16_bf16 v[64:79], v[100:103], v[10:13], v[64:79]
	s_waitcnt lgkmcnt(0)
	v_mfma_f32_32x32x16_bf16 v[48:63], v[92:95], v[10:13], v[48:63]
	ds_read2_b64 v[10:13], v14 offset0:136 offset1:138
	v_mfma_f32_32x32x16_bf16 v[32:47], v[100:103], v[88:91], v[32:47]
	s_waitcnt lgkmcnt(0)
	v_mfma_f32_32x32x16_bf16 v[64:79], v[10:13], v[6:9], v[64:79]
	v_mfma_f32_32x32x16_bf16 v[32:47], v[10:13], v[84:87], v[32:47]
	ds_read2_b64 v[10:13], v0 offset0:200 offset1:202
	s_waitcnt lgkmcnt(0)
	v_mfma_f32_32x32x16_bf16 v[48:63], v[10:13], v[6:9], v[48:63]
	ds_read2_b64 v[6:9], v14 offset0:140 offset1:142
	v_mfma_f32_32x32x16_bf16 v[16:31], v[92:95], v[88:91], v[16:31]
	s_waitcnt lgkmcnt(0)
	v_mfma_f32_32x32x16_bf16 v[64:79], v[6:9], v[2:5], v[64:79]
	v_mfma_f32_32x32x16_bf16 v[32:47], v[6:9], v[80:83], v[32:47]
	ds_read2_b64 v[6:9], v0 offset0:204 offset1:206
	v_mfma_f32_32x32x16_bf16 v[16:31], v[10:13], v[84:87], v[16:31]
	s_waitcnt lgkmcnt(0)
	v_mfma_f32_32x32x16_bf16 v[48:63], v[6:9], v[2:5], v[48:63]
	v_mfma_f32_32x32x16_bf16 v[16:31], v[6:9], v[80:83], v[16:31]
